# compress GEMM (64 workgroups, chip otherwise idle): one workgroup barrier per super-phase in its K-loop
# baseline (speedup 1.0000x reference)
.LBB0_654:
	s_cmp_lg_u64 s[16:17], 0
	s_cbranch_scc1 .LkA_654
.LkB_654:
	ds_read_b128 v[140:143], v150
	ds_read_b128 v[154:157], v150 offset:1024
	ds_read_b128 v[158:161], v150 offset:2048
	ds_read_b128 v[162:165], v150 offset:3072
	ds_read_b128 v[166:169], v151
	ds_read_b128 v[170:173], v151 offset:1024
	ds_read_b128 v[174:177], v151 offset:2048
	ds_read_b128 v[178:181], v151 offset:3072
	s_add_u32 s42, s40, 0xfff80080
	s_addc_u32 s43, s41, -1
	s_cmp_eq_u32 s67, 28
	s_cselect_b32 s45, s2, s43
	s_cselect_b32 s44, s31, s42
	s_cselect_b32 s43, s29, s66
	s_cselect_b32 s42, s64, s65
	v_lshl_add_u64 v[144:145], s[40:41], 0, v[136:137]
	s_add_i32 m0, s39, 0xc000
	ds_read_b128 v[182:185], v152
	ds_read_b128 v[186:189], v152 offset:1024
	ds_read_b128 v[190:193], v152 offset:2048
	ds_read_b128 v[194:197], v152 offset:3072
	ds_read_b128 v[198:201], v152 offset:4096
	ds_read_b128 v[202:205], v152 offset:5120
	ds_read_b128 v[206:209], v152 offset:6144
	ds_read_b128 v[210:213], v152 offset:7168
	global_load_lds_dwordx4 v[144:145], off
	v_lshl_add_u64 v[144:145], s[40:41], 0, v[138:139]
	s_add_i32 m0, s39, 0xe000
	s_nop 0
	global_load_lds_dwordx4 v[144:145], off
	s_waitcnt lgkmcnt(0)
	s_setprio 1
	s_waitcnt lgkmcnt(0)
	v_mfma_f32_16x16x32_bf16 v[124:127], v[140:143], v[182:185], v[124:127]
	v_mfma_f32_16x16x32_bf16 v[120:123], v[158:161], v[182:185], v[120:123]
	v_mfma_f32_16x16x32_bf16 v[108:111], v[140:143], v[190:193], v[108:111]
	v_mfma_f32_16x16x32_bf16 v[104:107], v[158:161], v[190:193], v[104:107]
	v_mfma_f32_16x16x32_bf16 v[92:95], v[140:143], v[198:201], v[92:95]
	v_mfma_f32_16x16x32_bf16 v[88:91], v[158:161], v[198:201], v[88:91]
	v_mfma_f32_16x16x32_bf16 v[76:79], v[140:143], v[206:209], v[76:79]
	v_mfma_f32_16x16x32_bf16 v[72:75], v[158:161], v[206:209], v[72:75]
	v_mfma_f32_16x16x32_bf16 v[124:127], v[154:157], v[186:189], v[124:127]
	v_mfma_f32_16x16x32_bf16 v[120:123], v[162:165], v[186:189], v[120:123]
	v_mfma_f32_16x16x32_bf16 v[108:111], v[154:157], v[194:197], v[108:111]
	v_mfma_f32_16x16x32_bf16 v[104:107], v[162:165], v[194:197], v[104:107]
	v_mfma_f32_16x16x32_bf16 v[92:95], v[154:157], v[202:205], v[92:95]
	v_mfma_f32_16x16x32_bf16 v[88:91], v[162:165], v[202:205], v[88:91]
	v_mfma_f32_16x16x32_bf16 v[76:79], v[154:157], v[210:213], v[76:79]
	v_mfma_f32_16x16x32_bf16 v[72:75], v[162:165], v[210:213], v[72:75]
	s_setprio 0
	s_setprio 1
	v_mfma_f32_16x16x32_bf16 v[116:119], v[166:169], v[182:185], v[116:119]
	v_mfma_f32_16x16x32_bf16 v[112:115], v[174:177], v[182:185], v[112:115]
	v_mfma_f32_16x16x32_bf16 v[100:103], v[166:169], v[190:193], v[100:103]
	v_mfma_f32_16x16x32_bf16 v[96:99], v[174:177], v[190:193], v[96:99]
	v_mfma_f32_16x16x32_bf16 v[84:87], v[166:169], v[198:201], v[84:87]
	v_mfma_f32_16x16x32_bf16 v[80:83], v[174:177], v[198:201], v[80:83]
	v_mfma_f32_16x16x32_bf16 v[68:71], v[166:169], v[206:209], v[68:71]
	v_mfma_f32_16x16x32_bf16 v[64:67], v[174:177], v[206:209], v[64:67]
	v_mfma_f32_16x16x32_bf16 v[116:119], v[170:173], v[186:189], v[116:119]
	v_mfma_f32_16x16x32_bf16 v[112:115], v[178:181], v[186:189], v[112:115]
	v_mfma_f32_16x16x32_bf16 v[100:103], v[170:173], v[194:197], v[100:103]
	v_mfma_f32_16x16x32_bf16 v[96:99], v[178:181], v[194:197], v[96:99]
	v_mfma_f32_16x16x32_bf16 v[84:87], v[170:173], v[202:205], v[84:87]
	v_mfma_f32_16x16x32_bf16 v[80:83], v[178:181], v[202:205], v[80:83]
	v_mfma_f32_16x16x32_bf16 v[68:71], v[170:173], v[210:213], v[68:71]
	v_mfma_f32_16x16x32_bf16 v[64:67], v[178:181], v[210:213], v[64:67]
	s_setprio 0
	s_waitcnt vmcnt(2)
	s_barrier
	s_add_i32 s68, s60, s47
	v_lshl_add_u64 v[144:145], s[42:43], 0, v[130:131]
	s_mov_b32 m0, s68
	ds_read_b128 v[182:185], v152 offset:16384
	ds_read_b128 v[186:189], v152 offset:17408
	ds_read_b128 v[190:193], v152 offset:18432
	ds_read_b128 v[194:197], v152 offset:19456
	ds_read_b128 v[198:201], v152 offset:20480
	ds_read_b128 v[202:205], v152 offset:21504
	ds_read_b128 v[206:209], v152 offset:22528
	ds_read_b128 v[210:213], v152 offset:23552
	global_load_lds_dwordx4 v[144:145], off
	s_add_i32 m0, s68, 0x2000
	s_add_u32 s68, s42, 0x80000
	v_lshl_add_u64 v[214:215], s[42:43], 0, v[134:135]
	s_addc_u32 s69, s43, 0
	s_add_i32 s70, s61, s47
	global_load_lds_dwordx4 v[214:215], off
	v_lshl_add_u64 v[216:217], s[68:69], 0, v[130:131]
	s_mov_b32 m0, s70
	v_lshl_add_u64 v[218:219], s[44:45], 0, v[132:133]
	global_load_lds_dwordx4 v[216:217], off
	v_lshl_add_u64 v[216:217], s[68:69], 0, v[134:135]
	s_add_i32 m0, s70, 0x2000
	s_nop 0
	global_load_lds_dwordx4 v[216:217], off
	v_lshl_add_u64 v[216:217], s[44:45], 0, v[128:129]
	s_mov_b32 m0, s39
	s_nop 0
	global_load_lds_dwordx4 v[216:217], off
	s_mov_b32 m0, s48
	s_nop 0
	global_load_lds_dwordx4 v[218:219], off
	s_waitcnt lgkmcnt(0)
	s_setprio 1
	s_waitcnt lgkmcnt(0)
	v_mfma_f32_16x16x32_bf16 v[60:63], v[140:143], v[182:185], v[60:63]
	v_mfma_f32_16x16x32_bf16 v[56:59], v[158:161], v[182:185], v[56:59]
	v_mfma_f32_16x16x32_bf16 v[44:47], v[140:143], v[190:193], v[44:47]
	v_mfma_f32_16x16x32_bf16 v[40:43], v[158:161], v[190:193], v[40:43]
	v_mfma_f32_16x16x32_bf16 v[28:31], v[140:143], v[198:201], v[28:31]
	v_mfma_f32_16x16x32_bf16 v[24:27], v[158:161], v[198:201], v[24:27]
	v_mfma_f32_16x16x32_bf16 v[12:15], v[140:143], v[206:209], v[12:15]
	v_mfma_f32_16x16x32_bf16 v[8:11], v[158:161], v[206:209], v[8:11]
	v_mfma_f32_16x16x32_bf16 v[60:63], v[154:157], v[186:189], v[60:63]
	v_mfma_f32_16x16x32_bf16 v[56:59], v[162:165], v[186:189], v[56:59]
	v_mfma_f32_16x16x32_bf16 v[44:47], v[154:157], v[194:197], v[44:47]
	v_mfma_f32_16x16x32_bf16 v[40:43], v[162:165], v[194:197], v[40:43]
	v_mfma_f32_16x16x32_bf16 v[28:31], v[154:157], v[202:205], v[28:31]
	v_mfma_f32_16x16x32_bf16 v[24:27], v[162:165], v[202:205], v[24:27]
	v_mfma_f32_16x16x32_bf16 v[12:15], v[154:157], v[210:213], v[12:15]
	v_mfma_f32_16x16x32_bf16 v[8:11], v[162:165], v[210:213], v[8:11]
	s_setprio 0
	s_setprio 1
	v_mfma_f32_16x16x32_bf16 v[52:55], v[166:169], v[182:185], v[52:55]
	v_mfma_f32_16x16x32_bf16 v[48:51], v[174:177], v[182:185], v[48:51]
	v_mfma_f32_16x16x32_bf16 v[36:39], v[166:169], v[190:193], v[36:39]
	v_mfma_f32_16x16x32_bf16 v[32:35], v[174:177], v[190:193], v[32:35]
	v_mfma_f32_16x16x32_bf16 v[20:23], v[166:169], v[198:201], v[20:23]
	v_mfma_f32_16x16x32_bf16 v[16:19], v[174:177], v[198:201], v[16:19]
	v_mfma_f32_16x16x32_bf16 v[4:7], v[166:169], v[206:209], v[4:7]
	v_mfma_f32_16x16x32_bf16 v[0:3], v[174:177], v[206:209], v[0:3]
	v_mfma_f32_16x16x32_bf16 v[52:55], v[170:173], v[186:189], v[52:55]
	v_mfma_f32_16x16x32_bf16 v[48:51], v[178:181], v[186:189], v[48:51]
	v_mfma_f32_16x16x32_bf16 v[36:39], v[170:173], v[194:197], v[36:39]
	v_mfma_f32_16x16x32_bf16 v[32:35], v[178:181], v[194:197], v[32:35]
	v_mfma_f32_16x16x32_bf16 v[20:23], v[170:173], v[202:205], v[20:23]
	v_mfma_f32_16x16x32_bf16 v[16:19], v[178:181], v[202:205], v[16:19]
	v_mfma_f32_16x16x32_bf16 v[4:7], v[170:173], v[210:213], v[4:7]
	v_mfma_f32_16x16x32_bf16 v[0:3], v[178:181], v[210:213], v[0:3]
	s_setprio 0
	s_waitcnt vmcnt(6)
	s_barrier
	s_add_i32 s68, 0, 0x18000
	v_add_u32_e32 v153, s68, v148
	s_add_i32 s69, 0, 0x1c000
	ds_read_b128 v[140:143], v153
	ds_read_b128 v[154:157], v153 offset:1024
	ds_read_b128 v[158:161], v153 offset:2048
	ds_read_b128 v[162:165], v153 offset:3072
	v_add_u32_e32 v153, s69, v148
	ds_read_b128 v[166:169], v153
	ds_read_b128 v[170:173], v153 offset:1024
	ds_read_b128 v[174:177], v153 offset:2048
	ds_read_b128 v[178:181], v153 offset:3072
	s_add_u32 s44, s44, 0x80000
	s_addc_u32 s45, s45, 0
	s_mov_b32 m0, s49
	v_lshl_add_u64 v[222:223], s[44:45], 0, v[128:129]
	ds_read_b128 v[182:185], v152 offset:32768
	ds_read_b128 v[186:189], v152 offset:33792
	ds_read_b128 v[190:193], v152 offset:34816
	ds_read_b128 v[194:197], v152 offset:35840
	ds_read_b128 v[198:201], v152 offset:36864
	ds_read_b128 v[202:205], v152 offset:37888
	ds_read_b128 v[206:209], v152 offset:38912
	ds_read_b128 v[210:213], v152 offset:39936
	global_load_lds_dwordx4 v[222:223], off
	v_lshl_add_u64 v[222:223], s[44:45], 0, v[132:133]
	s_mov_b32 m0, s50
	s_nop 0
	global_load_lds_dwordx4 v[222:223], off
	s_waitcnt lgkmcnt(0)
	s_setprio 1
	s_waitcnt lgkmcnt(0)
	v_mfma_f32_16x16x32_bf16 v[124:127], v[140:143], v[182:185], v[124:127]
	v_mfma_f32_16x16x32_bf16 v[120:123], v[158:161], v[182:185], v[120:123]
	v_mfma_f32_16x16x32_bf16 v[108:111], v[140:143], v[190:193], v[108:111]
	v_mfma_f32_16x16x32_bf16 v[104:107], v[158:161], v[190:193], v[104:107]
	v_mfma_f32_16x16x32_bf16 v[92:95], v[140:143], v[198:201], v[92:95]
	v_mfma_f32_16x16x32_bf16 v[88:91], v[158:161], v[198:201], v[88:91]
	v_mfma_f32_16x16x32_bf16 v[76:79], v[140:143], v[206:209], v[76:79]
	v_mfma_f32_16x16x32_bf16 v[72:75], v[158:161], v[206:209], v[72:75]
	v_mfma_f32_16x16x32_bf16 v[124:127], v[154:157], v[186:189], v[124:127]
	v_mfma_f32_16x16x32_bf16 v[120:123], v[162:165], v[186:189], v[120:123]
	v_mfma_f32_16x16x32_bf16 v[108:111], v[154:157], v[194:197], v[108:111]
	v_mfma_f32_16x16x32_bf16 v[104:107], v[162:165], v[194:197], v[104:107]
	v_mfma_f32_16x16x32_bf16 v[92:95], v[154:157], v[202:205], v[92:95]
	v_mfma_f32_16x16x32_bf16 v[88:91], v[162:165], v[202:205], v[88:91]
	v_mfma_f32_16x16x32_bf16 v[76:79], v[154:157], v[210:213], v[76:79]
	v_mfma_f32_16x16x32_bf16 v[72:75], v[162:165], v[210:213], v[72:75]
	s_setprio 0
	s_setprio 1
	v_mfma_f32_16x16x32_bf16 v[116:119], v[166:169], v[182:185], v[116:119]
	v_mfma_f32_16x16x32_bf16 v[112:115], v[174:177], v[182:185], v[112:115]
	v_mfma_f32_16x16x32_bf16 v[100:103], v[166:169], v[190:193], v[100:103]
	v_mfma_f32_16x16x32_bf16 v[96:99], v[174:177], v[190:193], v[96:99]
	v_mfma_f32_16x16x32_bf16 v[84:87], v[166:169], v[198:201], v[84:87]
	v_mfma_f32_16x16x32_bf16 v[80:83], v[174:177], v[198:201], v[80:83]
	v_mfma_f32_16x16x32_bf16 v[68:71], v[166:169], v[206:209], v[68:71]
	v_mfma_f32_16x16x32_bf16 v[64:67], v[174:177], v[206:209], v[64:67]
	v_mfma_f32_16x16x32_bf16 v[116:119], v[170:173], v[186:189], v[116:119]
	v_mfma_f32_16x16x32_bf16 v[112:115], v[178:181], v[186:189], v[112:115]
	v_mfma_f32_16x16x32_bf16 v[100:103], v[170:173], v[194:197], v[100:103]
	v_mfma_f32_16x16x32_bf16 v[96:99], v[178:181], v[194:197], v[96:99]
	v_mfma_f32_16x16x32_bf16 v[84:87], v[170:173], v[202:205], v[84:87]
	v_mfma_f32_16x16x32_bf16 v[80:83], v[178:181], v[202:205], v[80:83]
	v_mfma_f32_16x16x32_bf16 v[68:71], v[170:173], v[210:213], v[68:71]
	v_mfma_f32_16x16x32_bf16 v[64:67], v[178:181], v[210:213], v[64:67]
	s_setprio 0
	s_waitcnt vmcnt(2)
	s_barrier
	s_add_i32 s44, s68, s47
	v_lshl_add_u64 v[144:145], v[144:145], 0, s[14:15]
	s_mov_b32 m0, s44
	ds_read_b128 v[182:185], v152 offset:49152
	ds_read_b128 v[186:189], v152 offset:50176
	ds_read_b128 v[190:193], v152 offset:51200
	ds_read_b128 v[194:197], v152 offset:52224
	ds_read_b128 v[198:201], v152 offset:53248
	ds_read_b128 v[202:205], v152 offset:54272
	ds_read_b128 v[206:209], v152 offset:55296
	ds_read_b128 v[210:213], v152 offset:56320
	global_load_lds_dwordx4 v[144:145], off
	s_add_i32 m0, s44, 0x2000
	s_add_u32 s42, s42, 0x80080
	v_lshl_add_u64 v[144:145], v[214:215], 0, s[14:15]
	s_addc_u32 s43, s43, 0
	s_add_i32 s44, s69, s47
	global_load_lds_dwordx4 v[144:145], off
	v_lshl_add_u64 v[144:145], s[42:43], 0, v[130:131]
	s_mov_b32 m0, s44
	s_nop 0
	global_load_lds_dwordx4 v[144:145], off
	v_lshl_add_u64 v[144:145], s[42:43], 0, v[134:135]
	s_add_i32 m0, s44, 0x2000
	s_nop 0
	global_load_lds_dwordx4 v[144:145], off
	v_lshl_add_u64 v[144:145], v[216:217], 0, s[14:15]
	s_mov_b32 m0, s55
	s_nop 0
	global_load_lds_dwordx4 v[144:145], off
	v_lshl_add_u64 v[144:145], v[218:219], 0, s[14:15]
	s_mov_b32 m0, s57
	s_nop 0
	global_load_lds_dwordx4 v[144:145], off
	s_waitcnt lgkmcnt(0)
	s_setprio 1
	s_waitcnt lgkmcnt(0)
	v_mfma_f32_16x16x32_bf16 v[60:63], v[140:143], v[182:185], v[60:63]
	v_mfma_f32_16x16x32_bf16 v[56:59], v[158:161], v[182:185], v[56:59]
	v_mfma_f32_16x16x32_bf16 v[44:47], v[140:143], v[190:193], v[44:47]
	v_mfma_f32_16x16x32_bf16 v[40:43], v[158:161], v[190:193], v[40:43]
	v_mfma_f32_16x16x32_bf16 v[28:31], v[140:143], v[198:201], v[28:31]
	v_mfma_f32_16x16x32_bf16 v[24:27], v[158:161], v[198:201], v[24:27]
	v_mfma_f32_16x16x32_bf16 v[12:15], v[140:143], v[206:209], v[12:15]
	v_mfma_f32_16x16x32_bf16 v[8:11], v[158:161], v[206:209], v[8:11]
	v_mfma_f32_16x16x32_bf16 v[60:63], v[154:157], v[186:189], v[60:63]
	v_mfma_f32_16x16x32_bf16 v[56:59], v[162:165], v[186:189], v[56:59]
	v_mfma_f32_16x16x32_bf16 v[44:47], v[154:157], v[194:197], v[44:47]
	v_mfma_f32_16x16x32_bf16 v[40:43], v[162:165], v[194:197], v[40:43]
	v_mfma_f32_16x16x32_bf16 v[28:31], v[154:157], v[202:205], v[28:31]
	v_mfma_f32_16x16x32_bf16 v[24:27], v[162:165], v[202:205], v[24:27]
	v_mfma_f32_16x16x32_bf16 v[12:15], v[154:157], v[210:213], v[12:15]
	v_mfma_f32_16x16x32_bf16 v[8:11], v[162:165], v[210:213], v[8:11]
	s_setprio 0
	s_setprio 1
	v_mfma_f32_16x16x32_bf16 v[52:55], v[166:169], v[182:185], v[52:55]
	v_mfma_f32_16x16x32_bf16 v[48:51], v[174:177], v[182:185], v[48:51]
	v_mfma_f32_16x16x32_bf16 v[36:39], v[166:169], v[190:193], v[36:39]
	v_mfma_f32_16x16x32_bf16 v[32:35], v[174:177], v[190:193], v[32:35]
	v_mfma_f32_16x16x32_bf16 v[20:23], v[166:169], v[198:201], v[20:23]
	v_mfma_f32_16x16x32_bf16 v[16:19], v[174:177], v[198:201], v[16:19]
	v_mfma_f32_16x16x32_bf16 v[4:7], v[166:169], v[206:209], v[4:7]
	v_mfma_f32_16x16x32_bf16 v[0:3], v[174:177], v[206:209], v[0:3]
	v_mfma_f32_16x16x32_bf16 v[52:55], v[170:173], v[186:189], v[52:55]
	v_mfma_f32_16x16x32_bf16 v[48:51], v[178:181], v[186:189], v[48:51]
	v_mfma_f32_16x16x32_bf16 v[36:39], v[170:173], v[194:197], v[36:39]
	v_mfma_f32_16x16x32_bf16 v[32:35], v[178:181], v[194:197], v[32:35]
	v_mfma_f32_16x16x32_bf16 v[20:23], v[170:173], v[202:205], v[20:23]
	v_mfma_f32_16x16x32_bf16 v[16:19], v[178:181], v[202:205], v[16:19]
	v_mfma_f32_16x16x32_bf16 v[4:7], v[170:173], v[210:213], v[4:7]
	v_mfma_f32_16x16x32_bf16 v[0:3], v[178:181], v[210:213], v[0:3]
	s_setprio 0
	s_waitcnt vmcnt(6)
	s_barrier
	s_add_i32 s67, s67, 2
	s_add_u32 s40, s40, 0x100
	s_addc_u32 s41, s41, 0
	s_add_u32 s65, s65, 0x100
	s_addc_u32 s66, s66, 0
	s_cmp_gt_u32 s67, 29
	s_cbranch_scc0 .LkB_654
	s_branch .Lkx_654
.LkA_654:
	ds_read_b128 v[140:143], v150
	ds_read_b128 v[154:157], v150 offset:1024
	ds_read_b128 v[158:161], v150 offset:2048
	ds_read_b128 v[162:165], v150 offset:3072
	ds_read_b128 v[166:169], v151
	ds_read_b128 v[170:173], v151 offset:1024
	ds_read_b128 v[174:177], v151 offset:2048
	ds_read_b128 v[178:181], v151 offset:3072
	ds_read_b128 v[182:185], v152
	ds_read_b128 v[186:189], v152 offset:1024
	ds_read_b128 v[190:193], v152 offset:2048
	ds_read_b128 v[194:197], v152 offset:3072
	ds_read_b128 v[198:201], v152 offset:4096
	ds_read_b128 v[202:205], v152 offset:5120
	ds_read_b128 v[206:209], v152 offset:6144
	ds_read_b128 v[210:213], v152 offset:7168
	s_waitcnt vmcnt(6)
	s_waitcnt lgkmcnt(0)
	s_barrier
	s_add_u32 s42, s40, 0xfff80080
	s_addc_u32 s43, s41, -1
	s_cmp_eq_u32 s67, 28
	s_cselect_b32 s45, s2, s43
	s_cselect_b32 s44, s31, s42
	s_cselect_b32 s43, s29, s66
	s_cselect_b32 s42, s64, s65
	v_lshl_add_u64 v[144:145], s[40:41], 0, v[136:137]
	s_add_i32 m0, s39, 0xc000
	s_nop 0
	global_load_lds_dwordx4 v[144:145], off
	v_lshl_add_u64 v[144:145], s[40:41], 0, v[138:139]
	s_add_i32 m0, s39, 0xe000
	s_nop 0
	global_load_lds_dwordx4 v[144:145], off
	s_setprio 1
	s_waitcnt lgkmcnt(0)
	v_mfma_f32_16x16x32_bf16 v[124:127], v[140:143], v[182:185], v[124:127]
	v_mfma_f32_16x16x32_bf16 v[120:123], v[158:161], v[182:185], v[120:123]
	v_mfma_f32_16x16x32_bf16 v[108:111], v[140:143], v[190:193], v[108:111]
	v_mfma_f32_16x16x32_bf16 v[104:107], v[158:161], v[190:193], v[104:107]
	v_mfma_f32_16x16x32_bf16 v[92:95], v[140:143], v[198:201], v[92:95]
	v_mfma_f32_16x16x32_bf16 v[88:91], v[158:161], v[198:201], v[88:91]
	v_mfma_f32_16x16x32_bf16 v[76:79], v[140:143], v[206:209], v[76:79]
	v_mfma_f32_16x16x32_bf16 v[72:75], v[158:161], v[206:209], v[72:75]
	v_mfma_f32_16x16x32_bf16 v[124:127], v[154:157], v[186:189], v[124:127]
	v_mfma_f32_16x16x32_bf16 v[120:123], v[162:165], v[186:189], v[120:123]
	v_mfma_f32_16x16x32_bf16 v[108:111], v[154:157], v[194:197], v[108:111]
	v_mfma_f32_16x16x32_bf16 v[104:107], v[162:165], v[194:197], v[104:107]
	v_mfma_f32_16x16x32_bf16 v[92:95], v[154:157], v[202:205], v[92:95]
	v_mfma_f32_16x16x32_bf16 v[88:91], v[162:165], v[202:205], v[88:91]
	v_mfma_f32_16x16x32_bf16 v[76:79], v[154:157], v[210:213], v[76:79]
	v_mfma_f32_16x16x32_bf16 v[72:75], v[162:165], v[210:213], v[72:75]
	s_setprio 0
	s_setprio 1
	v_mfma_f32_16x16x32_bf16 v[116:119], v[166:169], v[182:185], v[116:119]
	v_mfma_f32_16x16x32_bf16 v[112:115], v[174:177], v[182:185], v[112:115]
	v_mfma_f32_16x16x32_bf16 v[100:103], v[166:169], v[190:193], v[100:103]
	v_mfma_f32_16x16x32_bf16 v[96:99], v[174:177], v[190:193], v[96:99]
	v_mfma_f32_16x16x32_bf16 v[84:87], v[166:169], v[198:201], v[84:87]
	v_mfma_f32_16x16x32_bf16 v[80:83], v[174:177], v[198:201], v[80:83]
	v_mfma_f32_16x16x32_bf16 v[68:71], v[166:169], v[206:209], v[68:71]
	v_mfma_f32_16x16x32_bf16 v[64:67], v[174:177], v[206:209], v[64:67]
	v_mfma_f32_16x16x32_bf16 v[116:119], v[170:173], v[186:189], v[116:119]
	v_mfma_f32_16x16x32_bf16 v[112:115], v[178:181], v[186:189], v[112:115]
	v_mfma_f32_16x16x32_bf16 v[100:103], v[170:173], v[194:197], v[100:103]
	v_mfma_f32_16x16x32_bf16 v[96:99], v[178:181], v[194:197], v[96:99]
	v_mfma_f32_16x16x32_bf16 v[84:87], v[170:173], v[202:205], v[84:87]
	v_mfma_f32_16x16x32_bf16 v[80:83], v[178:181], v[202:205], v[80:83]
	v_mfma_f32_16x16x32_bf16 v[68:71], v[170:173], v[210:213], v[68:71]
	v_mfma_f32_16x16x32_bf16 v[64:67], v[178:181], v[210:213], v[64:67]
	s_setprio 0
	ds_read_b128 v[182:185], v152 offset:16384
	ds_read_b128 v[186:189], v152 offset:17408
	ds_read_b128 v[190:193], v152 offset:18432
	ds_read_b128 v[194:197], v152 offset:19456
	ds_read_b128 v[198:201], v152 offset:20480
	ds_read_b128 v[202:205], v152 offset:21504
	ds_read_b128 v[206:209], v152 offset:22528
	ds_read_b128 v[210:213], v152 offset:23552
	s_waitcnt vmcnt(2)
	s_waitcnt lgkmcnt(0)
	s_barrier
	s_add_i32 s68, s60, s47
	v_lshl_add_u64 v[144:145], s[42:43], 0, v[130:131]
	s_mov_b32 m0, s68
	s_nop 0
	global_load_lds_dwordx4 v[144:145], off
	s_add_i32 m0, s68, 0x2000
	s_add_u32 s68, s42, 0x80000
	v_lshl_add_u64 v[214:215], s[42:43], 0, v[134:135]
	s_addc_u32 s69, s43, 0
	s_add_i32 s70, s61, s47
	global_load_lds_dwordx4 v[214:215], off
	v_lshl_add_u64 v[216:217], s[68:69], 0, v[130:131]
	s_mov_b32 m0, s70
	v_lshl_add_u64 v[218:219], s[44:45], 0, v[132:133]
	global_load_lds_dwordx4 v[216:217], off
	v_lshl_add_u64 v[216:217], s[68:69], 0, v[134:135]
	s_add_i32 m0, s70, 0x2000
	s_nop 0
	global_load_lds_dwordx4 v[216:217], off
	v_lshl_add_u64 v[216:217], s[44:45], 0, v[128:129]
	s_mov_b32 m0, s39
	s_nop 0
	global_load_lds_dwordx4 v[216:217], off
	s_mov_b32 m0, s48
	s_nop 0
	global_load_lds_dwordx4 v[218:219], off
	s_setprio 1
	s_waitcnt lgkmcnt(0)
	v_mfma_f32_16x16x32_bf16 v[60:63], v[140:143], v[182:185], v[60:63]
	v_mfma_f32_16x16x32_bf16 v[56:59], v[158:161], v[182:185], v[56:59]
	v_mfma_f32_16x16x32_bf16 v[44:47], v[140:143], v[190:193], v[44:47]
	v_mfma_f32_16x16x32_bf16 v[40:43], v[158:161], v[190:193], v[40:43]
	v_mfma_f32_16x16x32_bf16 v[28:31], v[140:143], v[198:201], v[28:31]
	v_mfma_f32_16x16x32_bf16 v[24:27], v[158:161], v[198:201], v[24:27]
	v_mfma_f32_16x16x32_bf16 v[12:15], v[140:143], v[206:209], v[12:15]
	v_mfma_f32_16x16x32_bf16 v[8:11], v[158:161], v[206:209], v[8:11]
	v_mfma_f32_16x16x32_bf16 v[60:63], v[154:157], v[186:189], v[60:63]
	v_mfma_f32_16x16x32_bf16 v[56:59], v[162:165], v[186:189], v[56:59]
	v_mfma_f32_16x16x32_bf16 v[44:47], v[154:157], v[194:197], v[44:47]
	v_mfma_f32_16x16x32_bf16 v[40:43], v[162:165], v[194:197], v[40:43]
	v_mfma_f32_16x16x32_bf16 v[28:31], v[154:157], v[202:205], v[28:31]
	v_mfma_f32_16x16x32_bf16 v[24:27], v[162:165], v[202:205], v[24:27]
	v_mfma_f32_16x16x32_bf16 v[12:15], v[154:157], v[210:213], v[12:15]
	v_mfma_f32_16x16x32_bf16 v[8:11], v[162:165], v[210:213], v[8:11]
	s_setprio 0
	s_setprio 1
	v_mfma_f32_16x16x32_bf16 v[52:55], v[166:169], v[182:185], v[52:55]
	v_mfma_f32_16x16x32_bf16 v[48:51], v[174:177], v[182:185], v[48:51]
	v_mfma_f32_16x16x32_bf16 v[36:39], v[166:169], v[190:193], v[36:39]
	v_mfma_f32_16x16x32_bf16 v[32:35], v[174:177], v[190:193], v[32:35]
	v_mfma_f32_16x16x32_bf16 v[20:23], v[166:169], v[198:201], v[20:23]
	v_mfma_f32_16x16x32_bf16 v[16:19], v[174:177], v[198:201], v[16:19]
	v_mfma_f32_16x16x32_bf16 v[4:7], v[166:169], v[206:209], v[4:7]
	v_mfma_f32_16x16x32_bf16 v[0:3], v[174:177], v[206:209], v[0:3]
	v_mfma_f32_16x16x32_bf16 v[52:55], v[170:173], v[186:189], v[52:55]
	v_mfma_f32_16x16x32_bf16 v[48:51], v[178:181], v[186:189], v[48:51]
	v_mfma_f32_16x16x32_bf16 v[36:39], v[170:173], v[194:197], v[36:39]
	v_mfma_f32_16x16x32_bf16 v[32:35], v[178:181], v[194:197], v[32:35]
	v_mfma_f32_16x16x32_bf16 v[20:23], v[170:173], v[202:205], v[20:23]
	v_mfma_f32_16x16x32_bf16 v[16:19], v[178:181], v[202:205], v[16:19]
	v_mfma_f32_16x16x32_bf16 v[4:7], v[170:173], v[210:213], v[4:7]
	v_mfma_f32_16x16x32_bf16 v[0:3], v[178:181], v[210:213], v[0:3]
	s_setprio 0
	s_add_i32 s68, 0, 0x18000
	v_add_u32_e32 v153, s68, v148
	s_add_i32 s69, 0, 0x1c000
	ds_read_b128 v[140:143], v153
	ds_read_b128 v[154:157], v153 offset:1024
	ds_read_b128 v[158:161], v153 offset:2048
	ds_read_b128 v[162:165], v153 offset:3072
	v_add_u32_e32 v153, s69, v148
	ds_read_b128 v[166:169], v153
	ds_read_b128 v[170:173], v153 offset:1024
	ds_read_b128 v[174:177], v153 offset:2048
	ds_read_b128 v[178:181], v153 offset:3072
	ds_read_b128 v[182:185], v152 offset:32768
	ds_read_b128 v[186:189], v152 offset:33792
	ds_read_b128 v[190:193], v152 offset:34816
	ds_read_b128 v[194:197], v152 offset:35840
	ds_read_b128 v[198:201], v152 offset:36864
	ds_read_b128 v[202:205], v152 offset:37888
	ds_read_b128 v[206:209], v152 offset:38912
	ds_read_b128 v[210:213], v152 offset:39936
	s_waitcnt vmcnt(6)
	s_waitcnt lgkmcnt(0)
	s_barrier
	s_add_u32 s44, s44, 0x80000
	s_addc_u32 s45, s45, 0
	s_mov_b32 m0, s49
	v_lshl_add_u64 v[222:223], s[44:45], 0, v[128:129]
	global_load_lds_dwordx4 v[222:223], off
	v_lshl_add_u64 v[222:223], s[44:45], 0, v[132:133]
	s_mov_b32 m0, s50
	s_nop 0
	global_load_lds_dwordx4 v[222:223], off
	s_setprio 1
	s_waitcnt lgkmcnt(0)
	v_mfma_f32_16x16x32_bf16 v[124:127], v[140:143], v[182:185], v[124:127]
	v_mfma_f32_16x16x32_bf16 v[120:123], v[158:161], v[182:185], v[120:123]
	v_mfma_f32_16x16x32_bf16 v[108:111], v[140:143], v[190:193], v[108:111]
	v_mfma_f32_16x16x32_bf16 v[104:107], v[158:161], v[190:193], v[104:107]
	v_mfma_f32_16x16x32_bf16 v[92:95], v[140:143], v[198:201], v[92:95]
	v_mfma_f32_16x16x32_bf16 v[88:91], v[158:161], v[198:201], v[88:91]
	v_mfma_f32_16x16x32_bf16 v[76:79], v[140:143], v[206:209], v[76:79]
	v_mfma_f32_16x16x32_bf16 v[72:75], v[158:161], v[206:209], v[72:75]
	v_mfma_f32_16x16x32_bf16 v[124:127], v[154:157], v[186:189], v[124:127]
	v_mfma_f32_16x16x32_bf16 v[120:123], v[162:165], v[186:189], v[120:123]
	v_mfma_f32_16x16x32_bf16 v[108:111], v[154:157], v[194:197], v[108:111]
	v_mfma_f32_16x16x32_bf16 v[104:107], v[162:165], v[194:197], v[104:107]
	v_mfma_f32_16x16x32_bf16 v[92:95], v[154:157], v[202:205], v[92:95]
	v_mfma_f32_16x16x32_bf16 v[88:91], v[162:165], v[202:205], v[88:91]
	v_mfma_f32_16x16x32_bf16 v[76:79], v[154:157], v[210:213], v[76:79]
	v_mfma_f32_16x16x32_bf16 v[72:75], v[162:165], v[210:213], v[72:75]
	s_setprio 0
	s_setprio 1
	v_mfma_f32_16x16x32_bf16 v[116:119], v[166:169], v[182:185], v[116:119]
	v_mfma_f32_16x16x32_bf16 v[112:115], v[174:177], v[182:185], v[112:115]
	v_mfma_f32_16x16x32_bf16 v[100:103], v[166:169], v[190:193], v[100:103]
	v_mfma_f32_16x16x32_bf16 v[96:99], v[174:177], v[190:193], v[96:99]
	v_mfma_f32_16x16x32_bf16 v[84:87], v[166:169], v[198:201], v[84:87]
	v_mfma_f32_16x16x32_bf16 v[80:83], v[174:177], v[198:201], v[80:83]
	v_mfma_f32_16x16x32_bf16 v[68:71], v[166:169], v[206:209], v[68:71]
	v_mfma_f32_16x16x32_bf16 v[64:67], v[174:177], v[206:209], v[64:67]
	v_mfma_f32_16x16x32_bf16 v[116:119], v[170:173], v[186:189], v[116:119]
	v_mfma_f32_16x16x32_bf16 v[112:115], v[178:181], v[186:189], v[112:115]
	v_mfma_f32_16x16x32_bf16 v[100:103], v[170:173], v[194:197], v[100:103]
	v_mfma_f32_16x16x32_bf16 v[96:99], v[178:181], v[194:197], v[96:99]
	v_mfma_f32_16x16x32_bf16 v[84:87], v[170:173], v[202:205], v[84:87]
	v_mfma_f32_16x16x32_bf16 v[80:83], v[178:181], v[202:205], v[80:83]
	v_mfma_f32_16x16x32_bf16 v[68:71], v[170:173], v[210:213], v[68:71]
	v_mfma_f32_16x16x32_bf16 v[64:67], v[178:181], v[210:213], v[64:67]
	s_setprio 0
	ds_read_b128 v[182:185], v152 offset:49152
	ds_read_b128 v[186:189], v152 offset:50176
	ds_read_b128 v[190:193], v152 offset:51200
	ds_read_b128 v[194:197], v152 offset:52224
	ds_read_b128 v[198:201], v152 offset:53248
	ds_read_b128 v[202:205], v152 offset:54272
	ds_read_b128 v[206:209], v152 offset:55296
	ds_read_b128 v[210:213], v152 offset:56320
	s_waitcnt vmcnt(2)
	s_waitcnt lgkmcnt(0)
	s_barrier
	s_add_i32 s44, s68, s47
	v_lshl_add_u64 v[144:145], v[144:145], 0, s[14:15]
	s_mov_b32 m0, s44
	s_nop 0
	global_load_lds_dwordx4 v[144:145], off
	s_add_i32 m0, s44, 0x2000
	s_add_u32 s42, s42, 0x80080
	v_lshl_add_u64 v[144:145], v[214:215], 0, s[14:15]
	s_addc_u32 s43, s43, 0
	s_add_i32 s44, s69, s47
	global_load_lds_dwordx4 v[144:145], off
	v_lshl_add_u64 v[144:145], s[42:43], 0, v[130:131]
	s_mov_b32 m0, s44
	s_nop 0
	global_load_lds_dwordx4 v[144:145], off
	v_lshl_add_u64 v[144:145], s[42:43], 0, v[134:135]
	s_add_i32 m0, s44, 0x2000
	s_nop 0
	global_load_lds_dwordx4 v[144:145], off
	v_lshl_add_u64 v[144:145], v[216:217], 0, s[14:15]
	s_mov_b32 m0, s55
	s_nop 0
	global_load_lds_dwordx4 v[144:145], off
	v_lshl_add_u64 v[144:145], v[218:219], 0, s[14:15]
	s_mov_b32 m0, s57
	s_nop 0
	global_load_lds_dwordx4 v[144:145], off
	s_setprio 1
	s_waitcnt lgkmcnt(0)
	v_mfma_f32_16x16x32_bf16 v[60:63], v[140:143], v[182:185], v[60:63]
	v_mfma_f32_16x16x32_bf16 v[56:59], v[158:161], v[182:185], v[56:59]
	v_mfma_f32_16x16x32_bf16 v[44:47], v[140:143], v[190:193], v[44:47]
	v_mfma_f32_16x16x32_bf16 v[40:43], v[158:161], v[190:193], v[40:43]
	v_mfma_f32_16x16x32_bf16 v[28:31], v[140:143], v[198:201], v[28:31]
	v_mfma_f32_16x16x32_bf16 v[24:27], v[158:161], v[198:201], v[24:27]
	v_mfma_f32_16x16x32_bf16 v[12:15], v[140:143], v[206:209], v[12:15]
	v_mfma_f32_16x16x32_bf16 v[8:11], v[158:161], v[206:209], v[8:11]
	v_mfma_f32_16x16x32_bf16 v[60:63], v[154:157], v[186:189], v[60:63]
	v_mfma_f32_16x16x32_bf16 v[56:59], v[162:165], v[186:189], v[56:59]
	v_mfma_f32_16x16x32_bf16 v[44:47], v[154:157], v[194:197], v[44:47]
	v_mfma_f32_16x16x32_bf16 v[40:43], v[162:165], v[194:197], v[40:43]
	v_mfma_f32_16x16x32_bf16 v[28:31], v[154:157], v[202:205], v[28:31]
	v_mfma_f32_16x16x32_bf16 v[24:27], v[162:165], v[202:205], v[24:27]
	v_mfma_f32_16x16x32_bf16 v[12:15], v[154:157], v[210:213], v[12:15]
	v_mfma_f32_16x16x32_bf16 v[8:11], v[162:165], v[210:213], v[8:11]
	s_setprio 0
	s_setprio 1
	v_mfma_f32_16x16x32_bf16 v[52:55], v[166:169], v[182:185], v[52:55]
	v_mfma_f32_16x16x32_bf16 v[48:51], v[174:177], v[182:185], v[48:51]
	v_mfma_f32_16x16x32_bf16 v[36:39], v[166:169], v[190:193], v[36:39]
	v_mfma_f32_16x16x32_bf16 v[32:35], v[174:177], v[190:193], v[32:35]
	v_mfma_f32_16x16x32_bf16 v[20:23], v[166:169], v[198:201], v[20:23]
	v_mfma_f32_16x16x32_bf16 v[16:19], v[174:177], v[198:201], v[16:19]
	v_mfma_f32_16x16x32_bf16 v[4:7], v[166:169], v[206:209], v[4:7]
	v_mfma_f32_16x16x32_bf16 v[0:3], v[174:177], v[206:209], v[0:3]
	v_mfma_f32_16x16x32_bf16 v[52:55], v[170:173], v[186:189], v[52:55]
	v_mfma_f32_16x16x32_bf16 v[48:51], v[178:181], v[186:189], v[48:51]
	v_mfma_f32_16x16x32_bf16 v[36:39], v[170:173], v[194:197], v[36:39]
	v_mfma_f32_16x16x32_bf16 v[32:35], v[178:181], v[194:197], v[32:35]
	v_mfma_f32_16x16x32_bf16 v[20:23], v[170:173], v[202:205], v[20:23]
	v_mfma_f32_16x16x32_bf16 v[16:19], v[178:181], v[202:205], v[16:19]
	v_mfma_f32_16x16x32_bf16 v[4:7], v[170:173], v[210:213], v[4:7]
	v_mfma_f32_16x16x32_bf16 v[0:3], v[178:181], v[210:213], v[0:3]
	s_setprio 0
	s_add_i32 s67, s67, 2
	s_add_u32 s40, s40, 0x100
	s_addc_u32 s41, s41, 0
	s_add_u32 s65, s65, 0x100
	s_addc_u32 s66, s66, 0
	s_cmp_gt_u32 s67, 29
	s_cbranch_scc0 .LkA_654
.Lkx_654:
	s_and_b64 vcc, exec, s[16:17]
	s_cbranch_vccz .LBB0_657
	s_barrier
